# P1 epilogue: per-row rstd scaling as packed f32 multiplies (same products, half the VALU instructions)
# baseline (speedup 1.0000x reference)
.LBB0_160:
	s_lshr_b32 s10, s8, 2
	s_cmp_eq_u32 s10, 4
	s_cbranch_scc1 .Lp1_oldepi
	v_and_b32_e32 v130, 63, v194
	v_lshrrev_b32_e32 v134, 6, v194
	v_lshrrev_b32_e32 v131, 3, v130
	v_and_b32_e32 v132, 7, v130
	v_xor_b32_e32 v133, v132, v131
	v_lshlrev_b32_e32 v133, 4, v133
	v_lshl_add_u32 v135, v131, 7, v133
	v_lshl_add_u32 v135, v134, 11, v135
	v_add_u32_e32 v135, 0x20000, v135
	v_and_b32_e32 v138, 15, v130
	v_lshrrev_b32_e32 v137, 4, v130
	v_lshrrev_b32_e32 v133, 1, v137
	v_bitop3_b32 v133, v133, v138, 7 bitop3:0x78
	v_lshlrev_b32_e32 v133, 4, v133
	v_lshl_add_u32 v136, v138, 7, v133
	v_and_b32_e32 v133, 1, v137
	v_lshl_add_u32 v136, v133, 3, v136
	v_lshl_add_u32 v136, v134, 11, v136
	v_add_u32_e32 v136, 0x20000, v136
	v_lshl_add_u32 v139, v212, 7, v131
	v_mul_u32_u24_e32 v139, 0x3000, v139
	v_lshl_add_u32 v139, v204, 7, v139
	v_lshl_add_u32 v139, v132, 4, v139
	s_sub_u32 s11, s92, s44
	s_mul_i32 s12, s6, 0x300000
	s_add_u32 s11, s11, s12
	s_lshl_b32 s12, s8, 9
	s_add_u32 s11, s11, s12
	s_cmp_lt_u32 s8, 4
	s_cselect_b64 s[12:13], -1, 0
	v_mov_b32_e32 v176, 1.0
	s_nop 0
	v_cndmask_b32_e64 v176, v176, v200, s[12:13]
	s_cmp_eq_u32 s10, 3
	s_cbranch_scc1 .Lp1_epi_act
	s_cmp_eq_u32 s10, 5
	s_cbranch_scc1 .Lp1_epi_act
	v_mul_f32_e32 v182, v176, v224
	v_pk_mul_f32 v[126:127], v[182:183], v[126:127] op_sel_hi:[0,1]
	v_pk_mul_f32 v[128:129], v[182:183], v[128:129] op_sel_hi:[0,1]
	v_pk_mul_f32 v[122:123], v[182:183], v[122:123] op_sel_hi:[0,1]
	v_pk_mul_f32 v[124:125], v[182:183], v[124:125] op_sel_hi:[0,1]
	v_pk_mul_f32 v[118:119], v[182:183], v[118:119] op_sel_hi:[0,1]
	v_pk_mul_f32 v[120:121], v[182:183], v[120:121] op_sel_hi:[0,1]
	v_pk_mul_f32 v[114:115], v[182:183], v[114:115] op_sel_hi:[0,1]
	v_pk_mul_f32 v[116:117], v[182:183], v[116:117] op_sel_hi:[0,1]
	v_cvt_pk_bf16_f32 v140, v126, v127
	v_cvt_pk_bf16_f32 v141, v128, v129
	v_cvt_pk_bf16_f32 v142, v122, v123
	v_cvt_pk_bf16_f32 v143, v124, v125
	v_cvt_pk_bf16_f32 v144, v118, v119
	v_cvt_pk_bf16_f32 v145, v120, v121
	v_cvt_pk_bf16_f32 v146, v114, v115
	v_cvt_pk_bf16_f32 v147, v116, v117
	ds_write_b64 v136, v[140:141]
	v_xor_b32_e32 v173, 0x20, v136
	ds_write_b64 v173, v[142:143]
	v_xor_b32_e32 v174, 0x40, v136
	ds_write_b64 v174, v[144:145]
	v_xor_b32_e32 v175, 0x60, v136
	ds_write_b64 v175, v[146:147]
	ds_read_b128 v[148:151], v135
	ds_read_b128 v[152:155], v135 offset:1024
	v_mul_f32_e32 v182, v176, v225
	v_pk_mul_f32 v[110:111], v[182:183], v[110:111] op_sel_hi:[0,1]
	v_pk_mul_f32 v[112:113], v[182:183], v[112:113] op_sel_hi:[0,1]
	v_pk_mul_f32 v[106:107], v[182:183], v[106:107] op_sel_hi:[0,1]
	v_pk_mul_f32 v[108:109], v[182:183], v[108:109] op_sel_hi:[0,1]
	v_pk_mul_f32 v[102:103], v[182:183], v[102:103] op_sel_hi:[0,1]
	v_pk_mul_f32 v[104:105], v[182:183], v[104:105] op_sel_hi:[0,1]
	v_pk_mul_f32 v[98:99], v[182:183], v[98:99] op_sel_hi:[0,1]
	v_pk_mul_f32 v[100:101], v[182:183], v[100:101] op_sel_hi:[0,1]
	v_cvt_pk_bf16_f32 v164, v110, v111
	v_cvt_pk_bf16_f32 v165, v112, v113
	v_cvt_pk_bf16_f32 v166, v106, v107
	v_cvt_pk_bf16_f32 v167, v108, v109
	v_cvt_pk_bf16_f32 v168, v102, v103
	v_cvt_pk_bf16_f32 v169, v104, v105
	v_cvt_pk_bf16_f32 v170, v98, v99
	v_cvt_pk_bf16_f32 v171, v100, v101
	ds_write_b64 v136, v[164:165]
	v_xor_b32_e32 v173, 0x20, v136
	ds_write_b64 v173, v[166:167]
	v_xor_b32_e32 v174, 0x40, v136
	ds_write_b64 v174, v[168:169]
	v_xor_b32_e32 v175, 0x60, v136
	ds_write_b64 v175, v[170:171]
	ds_read_b128 v[156:159], v135
	ds_read_b128 v[160:163], v135 offset:1024
	s_waitcnt lgkmcnt(6)
	buffer_store_dwordx4 v[148:151], v139, s[44:47], s11 offen
	s_add_u32 s11, s11, 0x18000
	buffer_store_dwordx4 v[152:155], v139, s[44:47], s11 offen
	s_add_u32 s11, s11, 0x18000
	v_mul_f32_e32 v182, v176, v226
	v_pk_mul_f32 v[94:95], v[182:183], v[94:95] op_sel_hi:[0,1]
	v_pk_mul_f32 v[96:97], v[182:183], v[96:97] op_sel_hi:[0,1]
	v_pk_mul_f32 v[90:91], v[182:183], v[90:91] op_sel_hi:[0,1]
	v_pk_mul_f32 v[92:93], v[182:183], v[92:93] op_sel_hi:[0,1]
	v_pk_mul_f32 v[86:87], v[182:183], v[86:87] op_sel_hi:[0,1]
	v_pk_mul_f32 v[88:89], v[182:183], v[88:89] op_sel_hi:[0,1]
	v_pk_mul_f32 v[82:83], v[182:183], v[82:83] op_sel_hi:[0,1]
	v_pk_mul_f32 v[84:85], v[182:183], v[84:85] op_sel_hi:[0,1]
	v_cvt_pk_bf16_f32 v140, v94, v95
	v_cvt_pk_bf16_f32 v141, v96, v97
	v_cvt_pk_bf16_f32 v142, v90, v91
	v_cvt_pk_bf16_f32 v143, v92, v93
	v_cvt_pk_bf16_f32 v144, v86, v87
	v_cvt_pk_bf16_f32 v145, v88, v89
	v_cvt_pk_bf16_f32 v146, v82, v83
	v_cvt_pk_bf16_f32 v147, v84, v85
	ds_write_b64 v136, v[140:141]
	v_xor_b32_e32 v173, 0x20, v136
	ds_write_b64 v173, v[142:143]
	v_xor_b32_e32 v174, 0x40, v136
	ds_write_b64 v174, v[144:145]
	v_xor_b32_e32 v175, 0x60, v136
	ds_write_b64 v175, v[146:147]
	ds_read_b128 v[148:151], v135
	ds_read_b128 v[152:155], v135 offset:1024
	s_waitcnt lgkmcnt(6)
	buffer_store_dwordx4 v[156:159], v139, s[44:47], s11 offen
	s_add_u32 s11, s11, 0x18000
	buffer_store_dwordx4 v[160:163], v139, s[44:47], s11 offen
	s_add_u32 s11, s11, 0x18000
	v_mul_f32_e32 v182, v176, v227
	v_pk_mul_f32 v[78:79], v[182:183], v[78:79] op_sel_hi:[0,1]
	v_pk_mul_f32 v[80:81], v[182:183], v[80:81] op_sel_hi:[0,1]
	v_pk_mul_f32 v[74:75], v[182:183], v[74:75] op_sel_hi:[0,1]
	v_pk_mul_f32 v[76:77], v[182:183], v[76:77] op_sel_hi:[0,1]
	v_pk_mul_f32 v[70:71], v[182:183], v[70:71] op_sel_hi:[0,1]
	v_pk_mul_f32 v[72:73], v[182:183], v[72:73] op_sel_hi:[0,1]
	v_pk_mul_f32 v[66:67], v[182:183], v[66:67] op_sel_hi:[0,1]
	v_pk_mul_f32 v[68:69], v[182:183], v[68:69] op_sel_hi:[0,1]
	v_cvt_pk_bf16_f32 v164, v78, v79
	v_cvt_pk_bf16_f32 v165, v80, v81
	v_cvt_pk_bf16_f32 v166, v74, v75
	v_cvt_pk_bf16_f32 v167, v76, v77
	v_cvt_pk_bf16_f32 v168, v70, v71
	v_cvt_pk_bf16_f32 v169, v72, v73
	v_cvt_pk_bf16_f32 v170, v66, v67
	v_cvt_pk_bf16_f32 v171, v68, v69
	ds_write_b64 v136, v[164:165]
	v_xor_b32_e32 v173, 0x20, v136
	ds_write_b64 v173, v[166:167]
	v_xor_b32_e32 v174, 0x40, v136
	ds_write_b64 v174, v[168:169]
	v_xor_b32_e32 v175, 0x60, v136
	ds_write_b64 v175, v[170:171]
	ds_read_b128 v[156:159], v135
	ds_read_b128 v[160:163], v135 offset:1024
	s_waitcnt lgkmcnt(6)
	buffer_store_dwordx4 v[148:151], v139, s[44:47], s11 offen
	s_add_u32 s11, s11, 0x18000
	buffer_store_dwordx4 v[152:155], v139, s[44:47], s11 offen
	s_add_u32 s11, s11, 0x18000
	v_mul_f32_e32 v182, v176, v228
	v_pk_mul_f32 v[62:63], v[182:183], v[62:63] op_sel_hi:[0,1]
	v_pk_mul_f32 v[64:65], v[182:183], v[64:65] op_sel_hi:[0,1]
	v_pk_mul_f32 v[58:59], v[182:183], v[58:59] op_sel_hi:[0,1]
	v_pk_mul_f32 v[60:61], v[182:183], v[60:61] op_sel_hi:[0,1]
	v_pk_mul_f32 v[54:55], v[182:183], v[54:55] op_sel_hi:[0,1]
	v_pk_mul_f32 v[56:57], v[182:183], v[56:57] op_sel_hi:[0,1]
	v_pk_mul_f32 v[50:51], v[182:183], v[50:51] op_sel_hi:[0,1]
	v_pk_mul_f32 v[52:53], v[182:183], v[52:53] op_sel_hi:[0,1]
	v_cvt_pk_bf16_f32 v140, v62, v63
	v_cvt_pk_bf16_f32 v141, v64, v65
	v_cvt_pk_bf16_f32 v142, v58, v59
	v_cvt_pk_bf16_f32 v143, v60, v61
	v_cvt_pk_bf16_f32 v144, v54, v55
	v_cvt_pk_bf16_f32 v145, v56, v57
	v_cvt_pk_bf16_f32 v146, v50, v51
	v_cvt_pk_bf16_f32 v147, v52, v53
	ds_write_b64 v136, v[140:141]
	v_xor_b32_e32 v173, 0x20, v136
	ds_write_b64 v173, v[142:143]
	v_xor_b32_e32 v174, 0x40, v136
	ds_write_b64 v174, v[144:145]
	v_xor_b32_e32 v175, 0x60, v136
	ds_write_b64 v175, v[146:147]
	ds_read_b128 v[148:151], v135
	ds_read_b128 v[152:155], v135 offset:1024
	s_waitcnt lgkmcnt(6)
	buffer_store_dwordx4 v[156:159], v139, s[44:47], s11 offen
	s_add_u32 s11, s11, 0x18000
	buffer_store_dwordx4 v[160:163], v139, s[44:47], s11 offen
	s_add_u32 s11, s11, 0x18000
	v_mul_f32_e32 v182, v176, v231
	v_pk_mul_f32 v[46:47], v[182:183], v[46:47] op_sel_hi:[0,1]
	v_pk_mul_f32 v[48:49], v[182:183], v[48:49] op_sel_hi:[0,1]
	v_pk_mul_f32 v[42:43], v[182:183], v[42:43] op_sel_hi:[0,1]
	v_pk_mul_f32 v[44:45], v[182:183], v[44:45] op_sel_hi:[0,1]
	v_pk_mul_f32 v[38:39], v[182:183], v[38:39] op_sel_hi:[0,1]
	v_pk_mul_f32 v[40:41], v[182:183], v[40:41] op_sel_hi:[0,1]
	v_pk_mul_f32 v[34:35], v[182:183], v[34:35] op_sel_hi:[0,1]
	v_pk_mul_f32 v[36:37], v[182:183], v[36:37] op_sel_hi:[0,1]
	v_cvt_pk_bf16_f32 v164, v46, v47
	v_cvt_pk_bf16_f32 v165, v48, v49
	v_cvt_pk_bf16_f32 v166, v42, v43
	v_cvt_pk_bf16_f32 v167, v44, v45
	v_cvt_pk_bf16_f32 v168, v38, v39
	v_cvt_pk_bf16_f32 v169, v40, v41
	v_cvt_pk_bf16_f32 v170, v34, v35
	v_cvt_pk_bf16_f32 v171, v36, v37
	ds_write_b64 v136, v[164:165]
	v_xor_b32_e32 v173, 0x20, v136
	ds_write_b64 v173, v[166:167]
	v_xor_b32_e32 v174, 0x40, v136
	ds_write_b64 v174, v[168:169]
	v_xor_b32_e32 v175, 0x60, v136
	ds_write_b64 v175, v[170:171]
	ds_read_b128 v[156:159], v135
	ds_read_b128 v[160:163], v135 offset:1024
	s_waitcnt lgkmcnt(6)
	buffer_store_dwordx4 v[148:151], v139, s[44:47], s11 offen
	s_add_u32 s11, s11, 0x18000
	buffer_store_dwordx4 v[152:155], v139, s[44:47], s11 offen
	s_add_u32 s11, s11, 0x18000
	v_mul_f32_e32 v182, v176, v254
	v_pk_mul_f32 v[30:31], v[182:183], v[30:31] op_sel_hi:[0,1]
	v_pk_mul_f32 v[32:33], v[182:183], v[32:33] op_sel_hi:[0,1]
	v_pk_mul_f32 v[26:27], v[182:183], v[26:27] op_sel_hi:[0,1]
	v_pk_mul_f32 v[28:29], v[182:183], v[28:29] op_sel_hi:[0,1]
	v_pk_mul_f32 v[22:23], v[182:183], v[22:23] op_sel_hi:[0,1]
	v_pk_mul_f32 v[24:25], v[182:183], v[24:25] op_sel_hi:[0,1]
	v_pk_mul_f32 v[18:19], v[182:183], v[18:19] op_sel_hi:[0,1]
	v_pk_mul_f32 v[20:21], v[182:183], v[20:21] op_sel_hi:[0,1]
	v_cvt_pk_bf16_f32 v140, v30, v31
	v_cvt_pk_bf16_f32 v141, v32, v33
	v_cvt_pk_bf16_f32 v142, v26, v27
	v_cvt_pk_bf16_f32 v143, v28, v29
	v_cvt_pk_bf16_f32 v144, v22, v23
	v_cvt_pk_bf16_f32 v145, v24, v25
	v_cvt_pk_bf16_f32 v146, v18, v19
	v_cvt_pk_bf16_f32 v147, v20, v21
	ds_write_b64 v136, v[140:141]
	v_xor_b32_e32 v173, 0x20, v136
	ds_write_b64 v173, v[142:143]
	v_xor_b32_e32 v174, 0x40, v136
	ds_write_b64 v174, v[144:145]
	v_xor_b32_e32 v175, 0x60, v136
	ds_write_b64 v175, v[146:147]
	ds_read_b128 v[148:151], v135
	ds_read_b128 v[152:155], v135 offset:1024
	s_waitcnt lgkmcnt(6)
	buffer_store_dwordx4 v[156:159], v139, s[44:47], s11 offen
	s_add_u32 s11, s11, 0x18000
	buffer_store_dwordx4 v[160:163], v139, s[44:47], s11 offen
	s_add_u32 s11, s11, 0x18000
	v_mul_f32_e32 v182, v176, v255
	v_pk_mul_f32 v[14:15], v[182:183], v[14:15] op_sel_hi:[0,1]
	v_pk_mul_f32 v[16:17], v[182:183], v[16:17] op_sel_hi:[0,1]
	v_pk_mul_f32 v[10:11], v[182:183], v[10:11] op_sel_hi:[0,1]
	v_pk_mul_f32 v[12:13], v[182:183], v[12:13] op_sel_hi:[0,1]
	v_pk_mul_f32 v[6:7], v[182:183], v[6:7] op_sel_hi:[0,1]
	v_pk_mul_f32 v[8:9], v[182:183], v[8:9] op_sel_hi:[0,1]
	v_pk_mul_f32 v[2:3], v[182:183], v[2:3] op_sel_hi:[0,1]
	v_pk_mul_f32 v[4:5], v[182:183], v[4:5] op_sel_hi:[0,1]
	v_cvt_pk_bf16_f32 v164, v14, v15
	v_cvt_pk_bf16_f32 v165, v16, v17
	v_cvt_pk_bf16_f32 v166, v10, v11
	v_cvt_pk_bf16_f32 v167, v12, v13
	v_cvt_pk_bf16_f32 v168, v6, v7
	v_cvt_pk_bf16_f32 v169, v8, v9
	v_cvt_pk_bf16_f32 v170, v2, v3
	v_cvt_pk_bf16_f32 v171, v4, v5
	ds_write_b64 v136, v[164:165]
	v_xor_b32_e32 v173, 0x20, v136
	ds_write_b64 v173, v[166:167]
	v_xor_b32_e32 v174, 0x40, v136
	ds_write_b64 v174, v[168:169]
	v_xor_b32_e32 v175, 0x60, v136
	ds_write_b64 v175, v[170:171]
	ds_read_b128 v[156:159], v135
	ds_read_b128 v[160:163], v135 offset:1024
	s_waitcnt lgkmcnt(6)
	buffer_store_dwordx4 v[148:151], v139, s[44:47], s11 offen
	s_add_u32 s11, s11, 0x18000
	buffer_store_dwordx4 v[152:155], v139, s[44:47], s11 offen
	s_add_u32 s11, s11, 0x18000
	s_waitcnt lgkmcnt(0)
	buffer_store_dwordx4 v[156:159], v139, s[44:47], s11 offen
	s_add_u32 s11, s11, 0x18000
	buffer_store_dwordx4 v[160:163], v139, s[44:47], s11 offen
	s_branch .LBB0_141
.Lp1_epi_act:
	v_mul_f32_e32 v182, v176, v224
	v_pk_mul_f32 v[126:127], v[182:183], v[126:127] op_sel_hi:[0,1]
	v_pk_mul_f32 v[128:129], v[182:183], v[128:129] op_sel_hi:[0,1]
	v_pk_mul_f32 v[122:123], v[182:183], v[122:123] op_sel_hi:[0,1]
	v_pk_mul_f32 v[124:125], v[182:183], v[124:125] op_sel_hi:[0,1]
	v_pk_mul_f32 v[118:119], v[182:183], v[118:119] op_sel_hi:[0,1]
	v_pk_mul_f32 v[120:121], v[182:183], v[120:121] op_sel_hi:[0,1]
	v_pk_mul_f32 v[114:115], v[182:183], v[114:115] op_sel_hi:[0,1]
	v_pk_mul_f32 v[116:117], v[182:183], v[116:117] op_sel_hi:[0,1]
	v_mul_f32_e32 v178, 0xbfb8aa3b, v126
	v_mul_f32_e32 v179, 0xbfb8aa3b, v127
	v_mul_f32_e32 v180, 0xbfb8aa3b, v128
	v_mul_f32_e32 v181, 0xbfb8aa3b, v129
	v_exp_f32_e32 v178, v178
	v_exp_f32_e32 v179, v179
	v_exp_f32_e32 v180, v180
	v_exp_f32_e32 v181, v181
	v_add_f32_e32 v178, 1.0, v178
	v_add_f32_e32 v179, 1.0, v179
	v_add_f32_e32 v180, 1.0, v180
	v_add_f32_e32 v181, 1.0, v181
	v_rcp_f32_e32 v178, v178
	v_rcp_f32_e32 v179, v179
	v_rcp_f32_e32 v180, v180
	v_rcp_f32_e32 v181, v181
	v_mul_f32_e32 v126, v126, v178
	v_mul_f32_e32 v127, v127, v179
	v_mul_f32_e32 v128, v128, v180
	v_mul_f32_e32 v129, v129, v181
	v_mul_f32_e32 v178, 0xbfb8aa3b, v122
	v_mul_f32_e32 v179, 0xbfb8aa3b, v123
	v_mul_f32_e32 v180, 0xbfb8aa3b, v124
	v_mul_f32_e32 v181, 0xbfb8aa3b, v125
	v_exp_f32_e32 v178, v178
	v_exp_f32_e32 v179, v179
	v_exp_f32_e32 v180, v180
	v_exp_f32_e32 v181, v181
	v_add_f32_e32 v178, 1.0, v178
	v_add_f32_e32 v179, 1.0, v179
	v_add_f32_e32 v180, 1.0, v180
	v_add_f32_e32 v181, 1.0, v181
	v_rcp_f32_e32 v178, v178
	v_rcp_f32_e32 v179, v179
	v_rcp_f32_e32 v180, v180
	v_rcp_f32_e32 v181, v181
	v_mul_f32_e32 v122, v122, v178
	v_mul_f32_e32 v123, v123, v179
	v_mul_f32_e32 v124, v124, v180
	v_mul_f32_e32 v125, v125, v181
	v_mul_f32_e32 v178, 0xbfb8aa3b, v118
	v_mul_f32_e32 v179, 0xbfb8aa3b, v119
	v_mul_f32_e32 v180, 0xbfb8aa3b, v120
	v_mul_f32_e32 v181, 0xbfb8aa3b, v121
	v_exp_f32_e32 v178, v178
	v_exp_f32_e32 v179, v179
	v_exp_f32_e32 v180, v180
	v_exp_f32_e32 v181, v181
	v_add_f32_e32 v178, 1.0, v178
	v_add_f32_e32 v179, 1.0, v179
	v_add_f32_e32 v180, 1.0, v180
	v_add_f32_e32 v181, 1.0, v181
	v_rcp_f32_e32 v178, v178
	v_rcp_f32_e32 v179, v179
	v_rcp_f32_e32 v180, v180
	v_rcp_f32_e32 v181, v181
	v_mul_f32_e32 v118, v118, v178
	v_mul_f32_e32 v119, v119, v179
	v_mul_f32_e32 v120, v120, v180
	v_mul_f32_e32 v121, v121, v181
	v_mul_f32_e32 v178, 0xbfb8aa3b, v114
	v_mul_f32_e32 v179, 0xbfb8aa3b, v115
	v_mul_f32_e32 v180, 0xbfb8aa3b, v116
	v_mul_f32_e32 v181, 0xbfb8aa3b, v117
	v_exp_f32_e32 v178, v178
	v_exp_f32_e32 v179, v179
	v_exp_f32_e32 v180, v180
	v_exp_f32_e32 v181, v181
	v_add_f32_e32 v178, 1.0, v178
	v_add_f32_e32 v179, 1.0, v179
	v_add_f32_e32 v180, 1.0, v180
	v_add_f32_e32 v181, 1.0, v181
	v_rcp_f32_e32 v178, v178
	v_rcp_f32_e32 v179, v179
	v_rcp_f32_e32 v180, v180
	v_rcp_f32_e32 v181, v181
	v_mul_f32_e32 v114, v114, v178
	v_mul_f32_e32 v115, v115, v179
	v_mul_f32_e32 v116, v116, v180
	v_mul_f32_e32 v117, v117, v181
	v_cvt_pk_bf16_f32 v140, v126, v127
	v_cvt_pk_bf16_f32 v141, v128, v129
	v_cvt_pk_bf16_f32 v142, v122, v123
	v_cvt_pk_bf16_f32 v143, v124, v125
	v_cvt_pk_bf16_f32 v144, v118, v119
	v_cvt_pk_bf16_f32 v145, v120, v121
	v_cvt_pk_bf16_f32 v146, v114, v115
	v_cvt_pk_bf16_f32 v147, v116, v117
	ds_write_b64 v136, v[140:141]
	v_xor_b32_e32 v173, 0x20, v136
	ds_write_b64 v173, v[142:143]
	v_xor_b32_e32 v174, 0x40, v136
	ds_write_b64 v174, v[144:145]
	v_xor_b32_e32 v175, 0x60, v136
	ds_write_b64 v175, v[146:147]
	ds_read_b128 v[148:151], v135
	ds_read_b128 v[152:155], v135 offset:1024
	v_mul_f32_e32 v182, v176, v225
	v_pk_mul_f32 v[110:111], v[182:183], v[110:111] op_sel_hi:[0,1]
	v_pk_mul_f32 v[112:113], v[182:183], v[112:113] op_sel_hi:[0,1]
	v_pk_mul_f32 v[106:107], v[182:183], v[106:107] op_sel_hi:[0,1]
	v_pk_mul_f32 v[108:109], v[182:183], v[108:109] op_sel_hi:[0,1]
	v_pk_mul_f32 v[102:103], v[182:183], v[102:103] op_sel_hi:[0,1]
	v_pk_mul_f32 v[104:105], v[182:183], v[104:105] op_sel_hi:[0,1]
	v_pk_mul_f32 v[98:99], v[182:183], v[98:99] op_sel_hi:[0,1]
	v_pk_mul_f32 v[100:101], v[182:183], v[100:101] op_sel_hi:[0,1]
	v_mul_f32_e32 v178, 0xbfb8aa3b, v110
	v_mul_f32_e32 v179, 0xbfb8aa3b, v111
	v_mul_f32_e32 v180, 0xbfb8aa3b, v112
	v_mul_f32_e32 v181, 0xbfb8aa3b, v113
	v_exp_f32_e32 v178, v178
	v_exp_f32_e32 v179, v179
	v_exp_f32_e32 v180, v180
	v_exp_f32_e32 v181, v181
	v_add_f32_e32 v178, 1.0, v178
	v_add_f32_e32 v179, 1.0, v179
	v_add_f32_e32 v180, 1.0, v180
	v_add_f32_e32 v181, 1.0, v181
	v_rcp_f32_e32 v178, v178
	v_rcp_f32_e32 v179, v179
	v_rcp_f32_e32 v180, v180
	v_rcp_f32_e32 v181, v181
	v_mul_f32_e32 v110, v110, v178
	v_mul_f32_e32 v111, v111, v179
	v_mul_f32_e32 v112, v112, v180
	v_mul_f32_e32 v113, v113, v181
	v_mul_f32_e32 v178, 0xbfb8aa3b, v106
	v_mul_f32_e32 v179, 0xbfb8aa3b, v107
	v_mul_f32_e32 v180, 0xbfb8aa3b, v108
	v_mul_f32_e32 v181, 0xbfb8aa3b, v109
	v_exp_f32_e32 v178, v178
	v_exp_f32_e32 v179, v179
	v_exp_f32_e32 v180, v180
	v_exp_f32_e32 v181, v181
	v_add_f32_e32 v178, 1.0, v178
	v_add_f32_e32 v179, 1.0, v179
	v_add_f32_e32 v180, 1.0, v180
	v_add_f32_e32 v181, 1.0, v181
	v_rcp_f32_e32 v178, v178
	v_rcp_f32_e32 v179, v179
	v_rcp_f32_e32 v180, v180
	v_rcp_f32_e32 v181, v181
	v_mul_f32_e32 v106, v106, v178
	v_mul_f32_e32 v107, v107, v179
	v_mul_f32_e32 v108, v108, v180
	v_mul_f32_e32 v109, v109, v181
	v_mul_f32_e32 v178, 0xbfb8aa3b, v102
	v_mul_f32_e32 v179, 0xbfb8aa3b, v103
	v_mul_f32_e32 v180, 0xbfb8aa3b, v104
	v_mul_f32_e32 v181, 0xbfb8aa3b, v105
	v_exp_f32_e32 v178, v178
	v_exp_f32_e32 v179, v179
	v_exp_f32_e32 v180, v180
	v_exp_f32_e32 v181, v181
	v_add_f32_e32 v178, 1.0, v178
	v_add_f32_e32 v179, 1.0, v179
	v_add_f32_e32 v180, 1.0, v180
	v_add_f32_e32 v181, 1.0, v181
	v_rcp_f32_e32 v178, v178
	v_rcp_f32_e32 v179, v179
	v_rcp_f32_e32 v180, v180
	v_rcp_f32_e32 v181, v181
	v_mul_f32_e32 v102, v102, v178
	v_mul_f32_e32 v103, v103, v179
	v_mul_f32_e32 v104, v104, v180
	v_mul_f32_e32 v105, v105, v181
	v_mul_f32_e32 v178, 0xbfb8aa3b, v98
	v_mul_f32_e32 v179, 0xbfb8aa3b, v99
	v_mul_f32_e32 v180, 0xbfb8aa3b, v100
	v_mul_f32_e32 v181, 0xbfb8aa3b, v101
	v_exp_f32_e32 v178, v178
	v_exp_f32_e32 v179, v179
	v_exp_f32_e32 v180, v180
	v_exp_f32_e32 v181, v181
	v_add_f32_e32 v178, 1.0, v178
	v_add_f32_e32 v179, 1.0, v179
	v_add_f32_e32 v180, 1.0, v180
	v_add_f32_e32 v181, 1.0, v181
	v_rcp_f32_e32 v178, v178
	v_rcp_f32_e32 v179, v179
	v_rcp_f32_e32 v180, v180
	v_rcp_f32_e32 v181, v181
	v_mul_f32_e32 v98, v98, v178
	v_mul_f32_e32 v99, v99, v179
	v_mul_f32_e32 v100, v100, v180
	v_mul_f32_e32 v101, v101, v181
	v_cvt_pk_bf16_f32 v164, v110, v111
	v_cvt_pk_bf16_f32 v165, v112, v113
	v_cvt_pk_bf16_f32 v166, v106, v107
	v_cvt_pk_bf16_f32 v167, v108, v109
	v_cvt_pk_bf16_f32 v168, v102, v103
	v_cvt_pk_bf16_f32 v169, v104, v105
	v_cvt_pk_bf16_f32 v170, v98, v99
	v_cvt_pk_bf16_f32 v171, v100, v101
	ds_write_b64 v136, v[164:165]
	v_xor_b32_e32 v173, 0x20, v136
	ds_write_b64 v173, v[166:167]
	v_xor_b32_e32 v174, 0x40, v136
	ds_write_b64 v174, v[168:169]
	v_xor_b32_e32 v175, 0x60, v136
	ds_write_b64 v175, v[170:171]
	ds_read_b128 v[156:159], v135
	ds_read_b128 v[160:163], v135 offset:1024
	s_waitcnt lgkmcnt(6)
	buffer_store_dwordx4 v[148:151], v139, s[44:47], s11 offen
	s_add_u32 s11, s11, 0x18000
	buffer_store_dwordx4 v[152:155], v139, s[44:47], s11 offen
	s_add_u32 s11, s11, 0x18000
	v_mul_f32_e32 v182, v176, v226
	v_pk_mul_f32 v[94:95], v[182:183], v[94:95] op_sel_hi:[0,1]
	v_pk_mul_f32 v[96:97], v[182:183], v[96:97] op_sel_hi:[0,1]
	v_pk_mul_f32 v[90:91], v[182:183], v[90:91] op_sel_hi:[0,1]
	v_pk_mul_f32 v[92:93], v[182:183], v[92:93] op_sel_hi:[0,1]
	v_pk_mul_f32 v[86:87], v[182:183], v[86:87] op_sel_hi:[0,1]
	v_pk_mul_f32 v[88:89], v[182:183], v[88:89] op_sel_hi:[0,1]
	v_pk_mul_f32 v[82:83], v[182:183], v[82:83] op_sel_hi:[0,1]
	v_pk_mul_f32 v[84:85], v[182:183], v[84:85] op_sel_hi:[0,1]
	v_mul_f32_e32 v178, 0xbfb8aa3b, v94
	v_mul_f32_e32 v179, 0xbfb8aa3b, v95
	v_mul_f32_e32 v180, 0xbfb8aa3b, v96
	v_mul_f32_e32 v181, 0xbfb8aa3b, v97
	v_exp_f32_e32 v178, v178
	v_exp_f32_e32 v179, v179
	v_exp_f32_e32 v180, v180
	v_exp_f32_e32 v181, v181
	v_add_f32_e32 v178, 1.0, v178
	v_add_f32_e32 v179, 1.0, v179
	v_add_f32_e32 v180, 1.0, v180
	v_add_f32_e32 v181, 1.0, v181
	v_rcp_f32_e32 v178, v178
	v_rcp_f32_e32 v179, v179
	v_rcp_f32_e32 v180, v180
	v_rcp_f32_e32 v181, v181
	v_mul_f32_e32 v94, v94, v178
	v_mul_f32_e32 v95, v95, v179
	v_mul_f32_e32 v96, v96, v180
	v_mul_f32_e32 v97, v97, v181
	v_mul_f32_e32 v178, 0xbfb8aa3b, v90
	v_mul_f32_e32 v179, 0xbfb8aa3b, v91
	v_mul_f32_e32 v180, 0xbfb8aa3b, v92
	v_mul_f32_e32 v181, 0xbfb8aa3b, v93
	v_exp_f32_e32 v178, v178
	v_exp_f32_e32 v179, v179
	v_exp_f32_e32 v180, v180
	v_exp_f32_e32 v181, v181
	v_add_f32_e32 v178, 1.0, v178
	v_add_f32_e32 v179, 1.0, v179
	v_add_f32_e32 v180, 1.0, v180
	v_add_f32_e32 v181, 1.0, v181
	v_rcp_f32_e32 v178, v178
	v_rcp_f32_e32 v179, v179
	v_rcp_f32_e32 v180, v180
	v_rcp_f32_e32 v181, v181
	v_mul_f32_e32 v90, v90, v178
	v_mul_f32_e32 v91, v91, v179
	v_mul_f32_e32 v92, v92, v180
	v_mul_f32_e32 v93, v93, v181
	v_mul_f32_e32 v178, 0xbfb8aa3b, v86
	v_mul_f32_e32 v179, 0xbfb8aa3b, v87
	v_mul_f32_e32 v180, 0xbfb8aa3b, v88
	v_mul_f32_e32 v181, 0xbfb8aa3b, v89
	v_exp_f32_e32 v178, v178
	v_exp_f32_e32 v179, v179
	v_exp_f32_e32 v180, v180
	v_exp_f32_e32 v181, v181
	v_add_f32_e32 v178, 1.0, v178
	v_add_f32_e32 v179, 1.0, v179
	v_add_f32_e32 v180, 1.0, v180
	v_add_f32_e32 v181, 1.0, v181
	v_rcp_f32_e32 v178, v178
	v_rcp_f32_e32 v179, v179
	v_rcp_f32_e32 v180, v180
	v_rcp_f32_e32 v181, v181
	v_mul_f32_e32 v86, v86, v178
	v_mul_f32_e32 v87, v87, v179
	v_mul_f32_e32 v88, v88, v180
	v_mul_f32_e32 v89, v89, v181
	v_mul_f32_e32 v178, 0xbfb8aa3b, v82
	v_mul_f32_e32 v179, 0xbfb8aa3b, v83
	v_mul_f32_e32 v180, 0xbfb8aa3b, v84
	v_mul_f32_e32 v181, 0xbfb8aa3b, v85
	v_exp_f32_e32 v178, v178
	v_exp_f32_e32 v179, v179
	v_exp_f32_e32 v180, v180
	v_exp_f32_e32 v181, v181
	v_add_f32_e32 v178, 1.0, v178
	v_add_f32_e32 v179, 1.0, v179
	v_add_f32_e32 v180, 1.0, v180
	v_add_f32_e32 v181, 1.0, v181
	v_rcp_f32_e32 v178, v178
	v_rcp_f32_e32 v179, v179
	v_rcp_f32_e32 v180, v180
	v_rcp_f32_e32 v181, v181
	v_mul_f32_e32 v82, v82, v178
	v_mul_f32_e32 v83, v83, v179
	v_mul_f32_e32 v84, v84, v180
	v_mul_f32_e32 v85, v85, v181
	v_cvt_pk_bf16_f32 v140, v94, v95
	v_cvt_pk_bf16_f32 v141, v96, v97
	v_cvt_pk_bf16_f32 v142, v90, v91
	v_cvt_pk_bf16_f32 v143, v92, v93
	v_cvt_pk_bf16_f32 v144, v86, v87
	v_cvt_pk_bf16_f32 v145, v88, v89
	v_cvt_pk_bf16_f32 v146, v82, v83
	v_cvt_pk_bf16_f32 v147, v84, v85
	ds_write_b64 v136, v[140:141]
	v_xor_b32_e32 v173, 0x20, v136
	ds_write_b64 v173, v[142:143]
	v_xor_b32_e32 v174, 0x40, v136
	ds_write_b64 v174, v[144:145]
	v_xor_b32_e32 v175, 0x60, v136
	ds_write_b64 v175, v[146:147]
	ds_read_b128 v[148:151], v135
	ds_read_b128 v[152:155], v135 offset:1024
	s_waitcnt lgkmcnt(6)
	buffer_store_dwordx4 v[156:159], v139, s[44:47], s11 offen
	s_add_u32 s11, s11, 0x18000
	buffer_store_dwordx4 v[160:163], v139, s[44:47], s11 offen
	s_add_u32 s11, s11, 0x18000
	v_mul_f32_e32 v182, v176, v227
	v_pk_mul_f32 v[78:79], v[182:183], v[78:79] op_sel_hi:[0,1]
	v_pk_mul_f32 v[80:81], v[182:183], v[80:81] op_sel_hi:[0,1]
	v_pk_mul_f32 v[74:75], v[182:183], v[74:75] op_sel_hi:[0,1]
	v_pk_mul_f32 v[76:77], v[182:183], v[76:77] op_sel_hi:[0,1]
	v_pk_mul_f32 v[70:71], v[182:183], v[70:71] op_sel_hi:[0,1]
	v_pk_mul_f32 v[72:73], v[182:183], v[72:73] op_sel_hi:[0,1]
	v_pk_mul_f32 v[66:67], v[182:183], v[66:67] op_sel_hi:[0,1]
	v_pk_mul_f32 v[68:69], v[182:183], v[68:69] op_sel_hi:[0,1]
	v_mul_f32_e32 v178, 0xbfb8aa3b, v78
	v_mul_f32_e32 v179, 0xbfb8aa3b, v79
	v_mul_f32_e32 v180, 0xbfb8aa3b, v80
	v_mul_f32_e32 v181, 0xbfb8aa3b, v81
	v_exp_f32_e32 v178, v178
	v_exp_f32_e32 v179, v179
	v_exp_f32_e32 v180, v180
	v_exp_f32_e32 v181, v181
	v_add_f32_e32 v178, 1.0, v178
	v_add_f32_e32 v179, 1.0, v179
	v_add_f32_e32 v180, 1.0, v180
	v_add_f32_e32 v181, 1.0, v181
	v_rcp_f32_e32 v178, v178
	v_rcp_f32_e32 v179, v179
	v_rcp_f32_e32 v180, v180
	v_rcp_f32_e32 v181, v181
	v_mul_f32_e32 v78, v78, v178
	v_mul_f32_e32 v79, v79, v179
	v_mul_f32_e32 v80, v80, v180
	v_mul_f32_e32 v81, v81, v181
	v_mul_f32_e32 v178, 0xbfb8aa3b, v74
	v_mul_f32_e32 v179, 0xbfb8aa3b, v75
	v_mul_f32_e32 v180, 0xbfb8aa3b, v76
	v_mul_f32_e32 v181, 0xbfb8aa3b, v77
	v_exp_f32_e32 v178, v178
	v_exp_f32_e32 v179, v179
	v_exp_f32_e32 v180, v180
	v_exp_f32_e32 v181, v181
	v_add_f32_e32 v178, 1.0, v178
	v_add_f32_e32 v179, 1.0, v179
	v_add_f32_e32 v180, 1.0, v180
	v_add_f32_e32 v181, 1.0, v181
	v_rcp_f32_e32 v178, v178
	v_rcp_f32_e32 v179, v179
	v_rcp_f32_e32 v180, v180
	v_rcp_f32_e32 v181, v181
	v_mul_f32_e32 v74, v74, v178
	v_mul_f32_e32 v75, v75, v179
	v_mul_f32_e32 v76, v76, v180
	v_mul_f32_e32 v77, v77, v181
	v_mul_f32_e32 v178, 0xbfb8aa3b, v70
	v_mul_f32_e32 v179, 0xbfb8aa3b, v71
	v_mul_f32_e32 v180, 0xbfb8aa3b, v72
	v_mul_f32_e32 v181, 0xbfb8aa3b, v73
	v_exp_f32_e32 v178, v178
	v_exp_f32_e32 v179, v179
	v_exp_f32_e32 v180, v180
	v_exp_f32_e32 v181, v181
	v_add_f32_e32 v178, 1.0, v178
	v_add_f32_e32 v179, 1.0, v179
	v_add_f32_e32 v180, 1.0, v180
	v_add_f32_e32 v181, 1.0, v181
	v_rcp_f32_e32 v178, v178
	v_rcp_f32_e32 v179, v179
	v_rcp_f32_e32 v180, v180
	v_rcp_f32_e32 v181, v181
	v_mul_f32_e32 v70, v70, v178
	v_mul_f32_e32 v71, v71, v179
	v_mul_f32_e32 v72, v72, v180
	v_mul_f32_e32 v73, v73, v181
	v_mul_f32_e32 v178, 0xbfb8aa3b, v66
	v_mul_f32_e32 v179, 0xbfb8aa3b, v67
	v_mul_f32_e32 v180, 0xbfb8aa3b, v68
	v_mul_f32_e32 v181, 0xbfb8aa3b, v69
	v_exp_f32_e32 v178, v178
	v_exp_f32_e32 v179, v179
	v_exp_f32_e32 v180, v180
	v_exp_f32_e32 v181, v181
	v_add_f32_e32 v178, 1.0, v178
	v_add_f32_e32 v179, 1.0, v179
	v_add_f32_e32 v180, 1.0, v180
	v_add_f32_e32 v181, 1.0, v181
	v_rcp_f32_e32 v178, v178
	v_rcp_f32_e32 v179, v179
	v_rcp_f32_e32 v180, v180
	v_rcp_f32_e32 v181, v181
	v_mul_f32_e32 v66, v66, v178
	v_mul_f32_e32 v67, v67, v179
	v_mul_f32_e32 v68, v68, v180
	v_mul_f32_e32 v69, v69, v181
	v_cvt_pk_bf16_f32 v164, v78, v79
	v_cvt_pk_bf16_f32 v165, v80, v81
	v_cvt_pk_bf16_f32 v166, v74, v75
	v_cvt_pk_bf16_f32 v167, v76, v77
	v_cvt_pk_bf16_f32 v168, v70, v71
	v_cvt_pk_bf16_f32 v169, v72, v73
	v_cvt_pk_bf16_f32 v170, v66, v67
	v_cvt_pk_bf16_f32 v171, v68, v69
	ds_write_b64 v136, v[164:165]
	v_xor_b32_e32 v173, 0x20, v136
	ds_write_b64 v173, v[166:167]
	v_xor_b32_e32 v174, 0x40, v136
	ds_write_b64 v174, v[168:169]
	v_xor_b32_e32 v175, 0x60, v136
	ds_write_b64 v175, v[170:171]
	ds_read_b128 v[156:159], v135
	ds_read_b128 v[160:163], v135 offset:1024
	s_waitcnt lgkmcnt(6)
	buffer_store_dwordx4 v[148:151], v139, s[44:47], s11 offen
	s_add_u32 s11, s11, 0x18000
	buffer_store_dwordx4 v[152:155], v139, s[44:47], s11 offen
	s_add_u32 s11, s11, 0x18000
	v_mul_f32_e32 v182, v176, v228
	v_pk_mul_f32 v[62:63], v[182:183], v[62:63] op_sel_hi:[0,1]
	v_pk_mul_f32 v[64:65], v[182:183], v[64:65] op_sel_hi:[0,1]
	v_pk_mul_f32 v[58:59], v[182:183], v[58:59] op_sel_hi:[0,1]
	v_pk_mul_f32 v[60:61], v[182:183], v[60:61] op_sel_hi:[0,1]
	v_pk_mul_f32 v[54:55], v[182:183], v[54:55] op_sel_hi:[0,1]
	v_pk_mul_f32 v[56:57], v[182:183], v[56:57] op_sel_hi:[0,1]
	v_pk_mul_f32 v[50:51], v[182:183], v[50:51] op_sel_hi:[0,1]
	v_pk_mul_f32 v[52:53], v[182:183], v[52:53] op_sel_hi:[0,1]
	v_mul_f32_e32 v178, 0xbfb8aa3b, v62
	v_mul_f32_e32 v179, 0xbfb8aa3b, v63
	v_mul_f32_e32 v180, 0xbfb8aa3b, v64
	v_mul_f32_e32 v181, 0xbfb8aa3b, v65
	v_exp_f32_e32 v178, v178
	v_exp_f32_e32 v179, v179
	v_exp_f32_e32 v180, v180
	v_exp_f32_e32 v181, v181
	v_add_f32_e32 v178, 1.0, v178
	v_add_f32_e32 v179, 1.0, v179
	v_add_f32_e32 v180, 1.0, v180
	v_add_f32_e32 v181, 1.0, v181
	v_rcp_f32_e32 v178, v178
	v_rcp_f32_e32 v179, v179
	v_rcp_f32_e32 v180, v180
	v_rcp_f32_e32 v181, v181
	v_mul_f32_e32 v62, v62, v178
	v_mul_f32_e32 v63, v63, v179
	v_mul_f32_e32 v64, v64, v180
	v_mul_f32_e32 v65, v65, v181
	v_mul_f32_e32 v178, 0xbfb8aa3b, v58
	v_mul_f32_e32 v179, 0xbfb8aa3b, v59
	v_mul_f32_e32 v180, 0xbfb8aa3b, v60
	v_mul_f32_e32 v181, 0xbfb8aa3b, v61
	v_exp_f32_e32 v178, v178
	v_exp_f32_e32 v179, v179
	v_exp_f32_e32 v180, v180
	v_exp_f32_e32 v181, v181
	v_add_f32_e32 v178, 1.0, v178
	v_add_f32_e32 v179, 1.0, v179
	v_add_f32_e32 v180, 1.0, v180
	v_add_f32_e32 v181, 1.0, v181
	v_rcp_f32_e32 v178, v178
	v_rcp_f32_e32 v179, v179
	v_rcp_f32_e32 v180, v180
	v_rcp_f32_e32 v181, v181
	v_mul_f32_e32 v58, v58, v178
	v_mul_f32_e32 v59, v59, v179
	v_mul_f32_e32 v60, v60, v180
	v_mul_f32_e32 v61, v61, v181
	v_mul_f32_e32 v178, 0xbfb8aa3b, v54
	v_mul_f32_e32 v179, 0xbfb8aa3b, v55
	v_mul_f32_e32 v180, 0xbfb8aa3b, v56
	v_mul_f32_e32 v181, 0xbfb8aa3b, v57
	v_exp_f32_e32 v178, v178
	v_exp_f32_e32 v179, v179
	v_exp_f32_e32 v180, v180
	v_exp_f32_e32 v181, v181
	v_add_f32_e32 v178, 1.0, v178
	v_add_f32_e32 v179, 1.0, v179
	v_add_f32_e32 v180, 1.0, v180
	v_add_f32_e32 v181, 1.0, v181
	v_rcp_f32_e32 v178, v178
	v_rcp_f32_e32 v179, v179
	v_rcp_f32_e32 v180, v180
	v_rcp_f32_e32 v181, v181
	v_mul_f32_e32 v54, v54, v178
	v_mul_f32_e32 v55, v55, v179
	v_mul_f32_e32 v56, v56, v180
	v_mul_f32_e32 v57, v57, v181
	v_mul_f32_e32 v178, 0xbfb8aa3b, v50
	v_mul_f32_e32 v179, 0xbfb8aa3b, v51
	v_mul_f32_e32 v180, 0xbfb8aa3b, v52
	v_mul_f32_e32 v181, 0xbfb8aa3b, v53
	v_exp_f32_e32 v178, v178
	v_exp_f32_e32 v179, v179
	v_exp_f32_e32 v180, v180
	v_exp_f32_e32 v181, v181
	v_add_f32_e32 v178, 1.0, v178
	v_add_f32_e32 v179, 1.0, v179
	v_add_f32_e32 v180, 1.0, v180
	v_add_f32_e32 v181, 1.0, v181
	v_rcp_f32_e32 v178, v178
	v_rcp_f32_e32 v179, v179
	v_rcp_f32_e32 v180, v180
	v_rcp_f32_e32 v181, v181
	v_mul_f32_e32 v50, v50, v178
	v_mul_f32_e32 v51, v51, v179
	v_mul_f32_e32 v52, v52, v180
	v_mul_f32_e32 v53, v53, v181
	v_cvt_pk_bf16_f32 v140, v62, v63
	v_cvt_pk_bf16_f32 v141, v64, v65
	v_cvt_pk_bf16_f32 v142, v58, v59
	v_cvt_pk_bf16_f32 v143, v60, v61
	v_cvt_pk_bf16_f32 v144, v54, v55
	v_cvt_pk_bf16_f32 v145, v56, v57
	v_cvt_pk_bf16_f32 v146, v50, v51
	v_cvt_pk_bf16_f32 v147, v52, v53
	ds_write_b64 v136, v[140:141]
	v_xor_b32_e32 v173, 0x20, v136
	ds_write_b64 v173, v[142:143]
	v_xor_b32_e32 v174, 0x40, v136
	ds_write_b64 v174, v[144:145]
	v_xor_b32_e32 v175, 0x60, v136
	ds_write_b64 v175, v[146:147]
	ds_read_b128 v[148:151], v135
	ds_read_b128 v[152:155], v135 offset:1024
	s_waitcnt lgkmcnt(6)
	buffer_store_dwordx4 v[156:159], v139, s[44:47], s11 offen
	s_add_u32 s11, s11, 0x18000
	buffer_store_dwordx4 v[160:163], v139, s[44:47], s11 offen
	s_add_u32 s11, s11, 0x18000
	v_mul_f32_e32 v182, v176, v231
	v_pk_mul_f32 v[46:47], v[182:183], v[46:47] op_sel_hi:[0,1]
	v_pk_mul_f32 v[48:49], v[182:183], v[48:49] op_sel_hi:[0,1]
	v_pk_mul_f32 v[42:43], v[182:183], v[42:43] op_sel_hi:[0,1]
	v_pk_mul_f32 v[44:45], v[182:183], v[44:45] op_sel_hi:[0,1]
	v_pk_mul_f32 v[38:39], v[182:183], v[38:39] op_sel_hi:[0,1]
	v_pk_mul_f32 v[40:41], v[182:183], v[40:41] op_sel_hi:[0,1]
	v_pk_mul_f32 v[34:35], v[182:183], v[34:35] op_sel_hi:[0,1]
	v_pk_mul_f32 v[36:37], v[182:183], v[36:37] op_sel_hi:[0,1]
	v_mul_f32_e32 v178, 0xbfb8aa3b, v46
	v_mul_f32_e32 v179, 0xbfb8aa3b, v47
	v_mul_f32_e32 v180, 0xbfb8aa3b, v48
	v_mul_f32_e32 v181, 0xbfb8aa3b, v49
	v_exp_f32_e32 v178, v178
	v_exp_f32_e32 v179, v179
	v_exp_f32_e32 v180, v180
	v_exp_f32_e32 v181, v181
	v_add_f32_e32 v178, 1.0, v178
	v_add_f32_e32 v179, 1.0, v179
	v_add_f32_e32 v180, 1.0, v180
	v_add_f32_e32 v181, 1.0, v181
	v_rcp_f32_e32 v178, v178
	v_rcp_f32_e32 v179, v179
	v_rcp_f32_e32 v180, v180
	v_rcp_f32_e32 v181, v181
	v_mul_f32_e32 v46, v46, v178
	v_mul_f32_e32 v47, v47, v179
	v_mul_f32_e32 v48, v48, v180
	v_mul_f32_e32 v49, v49, v181
	v_mul_f32_e32 v178, 0xbfb8aa3b, v42
	v_mul_f32_e32 v179, 0xbfb8aa3b, v43
	v_mul_f32_e32 v180, 0xbfb8aa3b, v44
	v_mul_f32_e32 v181, 0xbfb8aa3b, v45
	v_exp_f32_e32 v178, v178
	v_exp_f32_e32 v179, v179
	v_exp_f32_e32 v180, v180
	v_exp_f32_e32 v181, v181
	v_add_f32_e32 v178, 1.0, v178
	v_add_f32_e32 v179, 1.0, v179
	v_add_f32_e32 v180, 1.0, v180
	v_add_f32_e32 v181, 1.0, v181
	v_rcp_f32_e32 v178, v178
	v_rcp_f32_e32 v179, v179
	v_rcp_f32_e32 v180, v180
	v_rcp_f32_e32 v181, v181
	v_mul_f32_e32 v42, v42, v178
	v_mul_f32_e32 v43, v43, v179
	v_mul_f32_e32 v44, v44, v180
	v_mul_f32_e32 v45, v45, v181
	v_mul_f32_e32 v178, 0xbfb8aa3b, v38
	v_mul_f32_e32 v179, 0xbfb8aa3b, v39
	v_mul_f32_e32 v180, 0xbfb8aa3b, v40
	v_mul_f32_e32 v181, 0xbfb8aa3b, v41
	v_exp_f32_e32 v178, v178
	v_exp_f32_e32 v179, v179
	v_exp_f32_e32 v180, v180
	v_exp_f32_e32 v181, v181
	v_add_f32_e32 v178, 1.0, v178
	v_add_f32_e32 v179, 1.0, v179
	v_add_f32_e32 v180, 1.0, v180
	v_add_f32_e32 v181, 1.0, v181
	v_rcp_f32_e32 v178, v178
	v_rcp_f32_e32 v179, v179
	v_rcp_f32_e32 v180, v180
	v_rcp_f32_e32 v181, v181
	v_mul_f32_e32 v38, v38, v178
	v_mul_f32_e32 v39, v39, v179
	v_mul_f32_e32 v40, v40, v180
	v_mul_f32_e32 v41, v41, v181
	v_mul_f32_e32 v178, 0xbfb8aa3b, v34
	v_mul_f32_e32 v179, 0xbfb8aa3b, v35
	v_mul_f32_e32 v180, 0xbfb8aa3b, v36
	v_mul_f32_e32 v181, 0xbfb8aa3b, v37
	v_exp_f32_e32 v178, v178
	v_exp_f32_e32 v179, v179
	v_exp_f32_e32 v180, v180
	v_exp_f32_e32 v181, v181
	v_add_f32_e32 v178, 1.0, v178
	v_add_f32_e32 v179, 1.0, v179
	v_add_f32_e32 v180, 1.0, v180
	v_add_f32_e32 v181, 1.0, v181
	v_rcp_f32_e32 v178, v178
	v_rcp_f32_e32 v179, v179
	v_rcp_f32_e32 v180, v180
	v_rcp_f32_e32 v181, v181
	v_mul_f32_e32 v34, v34, v178
	v_mul_f32_e32 v35, v35, v179
	v_mul_f32_e32 v36, v36, v180
	v_mul_f32_e32 v37, v37, v181
	v_cvt_pk_bf16_f32 v164, v46, v47
	v_cvt_pk_bf16_f32 v165, v48, v49
	v_cvt_pk_bf16_f32 v166, v42, v43
	v_cvt_pk_bf16_f32 v167, v44, v45
	v_cvt_pk_bf16_f32 v168, v38, v39
	v_cvt_pk_bf16_f32 v169, v40, v41
	v_cvt_pk_bf16_f32 v170, v34, v35
	v_cvt_pk_bf16_f32 v171, v36, v37
	ds_write_b64 v136, v[164:165]
	v_xor_b32_e32 v173, 0x20, v136
	ds_write_b64 v173, v[166:167]
	v_xor_b32_e32 v174, 0x40, v136
	ds_write_b64 v174, v[168:169]
	v_xor_b32_e32 v175, 0x60, v136
	ds_write_b64 v175, v[170:171]
	ds_read_b128 v[156:159], v135
	ds_read_b128 v[160:163], v135 offset:1024
	s_waitcnt lgkmcnt(6)
	buffer_store_dwordx4 v[148:151], v139, s[44:47], s11 offen
	s_add_u32 s11, s11, 0x18000
	buffer_store_dwordx4 v[152:155], v139, s[44:47], s11 offen
	s_add_u32 s11, s11, 0x18000
	v_mul_f32_e32 v182, v176, v254
	v_pk_mul_f32 v[30:31], v[182:183], v[30:31] op_sel_hi:[0,1]
	v_pk_mul_f32 v[32:33], v[182:183], v[32:33] op_sel_hi:[0,1]
	v_pk_mul_f32 v[26:27], v[182:183], v[26:27] op_sel_hi:[0,1]
	v_pk_mul_f32 v[28:29], v[182:183], v[28:29] op_sel_hi:[0,1]
	v_pk_mul_f32 v[22:23], v[182:183], v[22:23] op_sel_hi:[0,1]
	v_pk_mul_f32 v[24:25], v[182:183], v[24:25] op_sel_hi:[0,1]
	v_pk_mul_f32 v[18:19], v[182:183], v[18:19] op_sel_hi:[0,1]
	v_pk_mul_f32 v[20:21], v[182:183], v[20:21] op_sel_hi:[0,1]
	v_mul_f32_e32 v178, 0xbfb8aa3b, v30
	v_mul_f32_e32 v179, 0xbfb8aa3b, v31
	v_mul_f32_e32 v180, 0xbfb8aa3b, v32
	v_mul_f32_e32 v181, 0xbfb8aa3b, v33
	v_exp_f32_e32 v178, v178
	v_exp_f32_e32 v179, v179
	v_exp_f32_e32 v180, v180
	v_exp_f32_e32 v181, v181
	v_add_f32_e32 v178, 1.0, v178
	v_add_f32_e32 v179, 1.0, v179
	v_add_f32_e32 v180, 1.0, v180
	v_add_f32_e32 v181, 1.0, v181
	v_rcp_f32_e32 v178, v178
	v_rcp_f32_e32 v179, v179
	v_rcp_f32_e32 v180, v180
	v_rcp_f32_e32 v181, v181
	v_mul_f32_e32 v30, v30, v178
	v_mul_f32_e32 v31, v31, v179
	v_mul_f32_e32 v32, v32, v180
	v_mul_f32_e32 v33, v33, v181
	v_mul_f32_e32 v178, 0xbfb8aa3b, v26
	v_mul_f32_e32 v179, 0xbfb8aa3b, v27
	v_mul_f32_e32 v180, 0xbfb8aa3b, v28
	v_mul_f32_e32 v181, 0xbfb8aa3b, v29
	v_exp_f32_e32 v178, v178
	v_exp_f32_e32 v179, v179
	v_exp_f32_e32 v180, v180
	v_exp_f32_e32 v181, v181
	v_add_f32_e32 v178, 1.0, v178
	v_add_f32_e32 v179, 1.0, v179
	v_add_f32_e32 v180, 1.0, v180
	v_add_f32_e32 v181, 1.0, v181
	v_rcp_f32_e32 v178, v178
	v_rcp_f32_e32 v179, v179
	v_rcp_f32_e32 v180, v180
	v_rcp_f32_e32 v181, v181
	v_mul_f32_e32 v26, v26, v178
	v_mul_f32_e32 v27, v27, v179
	v_mul_f32_e32 v28, v28, v180
	v_mul_f32_e32 v29, v29, v181
	v_mul_f32_e32 v178, 0xbfb8aa3b, v22
	v_mul_f32_e32 v179, 0xbfb8aa3b, v23
	v_mul_f32_e32 v180, 0xbfb8aa3b, v24
	v_mul_f32_e32 v181, 0xbfb8aa3b, v25
	v_exp_f32_e32 v178, v178
	v_exp_f32_e32 v179, v179
	v_exp_f32_e32 v180, v180
	v_exp_f32_e32 v181, v181
	v_add_f32_e32 v178, 1.0, v178
	v_add_f32_e32 v179, 1.0, v179
	v_add_f32_e32 v180, 1.0, v180
	v_add_f32_e32 v181, 1.0, v181
	v_rcp_f32_e32 v178, v178
	v_rcp_f32_e32 v179, v179
	v_rcp_f32_e32 v180, v180
	v_rcp_f32_e32 v181, v181
	v_mul_f32_e32 v22, v22, v178
	v_mul_f32_e32 v23, v23, v179
	v_mul_f32_e32 v24, v24, v180
	v_mul_f32_e32 v25, v25, v181
	v_mul_f32_e32 v178, 0xbfb8aa3b, v18
	v_mul_f32_e32 v179, 0xbfb8aa3b, v19
	v_mul_f32_e32 v180, 0xbfb8aa3b, v20
	v_mul_f32_e32 v181, 0xbfb8aa3b, v21
	v_exp_f32_e32 v178, v178
	v_exp_f32_e32 v179, v179
	v_exp_f32_e32 v180, v180
	v_exp_f32_e32 v181, v181
	v_add_f32_e32 v178, 1.0, v178
	v_add_f32_e32 v179, 1.0, v179
	v_add_f32_e32 v180, 1.0, v180
	v_add_f32_e32 v181, 1.0, v181
	v_rcp_f32_e32 v178, v178
	v_rcp_f32_e32 v179, v179
	v_rcp_f32_e32 v180, v180
	v_rcp_f32_e32 v181, v181
	v_mul_f32_e32 v18, v18, v178
	v_mul_f32_e32 v19, v19, v179
	v_mul_f32_e32 v20, v20, v180
	v_mul_f32_e32 v21, v21, v181
	v_cvt_pk_bf16_f32 v140, v30, v31
	v_cvt_pk_bf16_f32 v141, v32, v33
	v_cvt_pk_bf16_f32 v142, v26, v27
	v_cvt_pk_bf16_f32 v143, v28, v29
	v_cvt_pk_bf16_f32 v144, v22, v23
	v_cvt_pk_bf16_f32 v145, v24, v25
	v_cvt_pk_bf16_f32 v146, v18, v19
	v_cvt_pk_bf16_f32 v147, v20, v21
	ds_write_b64 v136, v[140:141]
	v_xor_b32_e32 v173, 0x20, v136
	ds_write_b64 v173, v[142:143]
	v_xor_b32_e32 v174, 0x40, v136
	ds_write_b64 v174, v[144:145]
	v_xor_b32_e32 v175, 0x60, v136
	ds_write_b64 v175, v[146:147]
	ds_read_b128 v[148:151], v135
	ds_read_b128 v[152:155], v135 offset:1024
	s_waitcnt lgkmcnt(6)
	buffer_store_dwordx4 v[156:159], v139, s[44:47], s11 offen
	s_add_u32 s11, s11, 0x18000
	buffer_store_dwordx4 v[160:163], v139, s[44:47], s11 offen
	s_add_u32 s11, s11, 0x18000
	v_mul_f32_e32 v182, v176, v255
	v_pk_mul_f32 v[14:15], v[182:183], v[14:15] op_sel_hi:[0,1]
	v_pk_mul_f32 v[16:17], v[182:183], v[16:17] op_sel_hi:[0,1]
	v_pk_mul_f32 v[10:11], v[182:183], v[10:11] op_sel_hi:[0,1]
	v_pk_mul_f32 v[12:13], v[182:183], v[12:13] op_sel_hi:[0,1]
	v_pk_mul_f32 v[6:7], v[182:183], v[6:7] op_sel_hi:[0,1]
	v_pk_mul_f32 v[8:9], v[182:183], v[8:9] op_sel_hi:[0,1]
	v_pk_mul_f32 v[2:3], v[182:183], v[2:3] op_sel_hi:[0,1]
	v_pk_mul_f32 v[4:5], v[182:183], v[4:5] op_sel_hi:[0,1]
	v_mul_f32_e32 v178, 0xbfb8aa3b, v14
	v_mul_f32_e32 v179, 0xbfb8aa3b, v15
	v_mul_f32_e32 v180, 0xbfb8aa3b, v16
	v_mul_f32_e32 v181, 0xbfb8aa3b, v17
	v_exp_f32_e32 v178, v178
	v_exp_f32_e32 v179, v179
	v_exp_f32_e32 v180, v180
	v_exp_f32_e32 v181, v181
	v_add_f32_e32 v178, 1.0, v178
	v_add_f32_e32 v179, 1.0, v179
	v_add_f32_e32 v180, 1.0, v180
	v_add_f32_e32 v181, 1.0, v181
	v_rcp_f32_e32 v178, v178
	v_rcp_f32_e32 v179, v179
	v_rcp_f32_e32 v180, v180
	v_rcp_f32_e32 v181, v181
	v_mul_f32_e32 v14, v14, v178
	v_mul_f32_e32 v15, v15, v179
	v_mul_f32_e32 v16, v16, v180
	v_mul_f32_e32 v17, v17, v181
	v_mul_f32_e32 v178, 0xbfb8aa3b, v10
	v_mul_f32_e32 v179, 0xbfb8aa3b, v11
	v_mul_f32_e32 v180, 0xbfb8aa3b, v12
	v_mul_f32_e32 v181, 0xbfb8aa3b, v13
	v_exp_f32_e32 v178, v178
	v_exp_f32_e32 v179, v179
	v_exp_f32_e32 v180, v180
	v_exp_f32_e32 v181, v181
	v_add_f32_e32 v178, 1.0, v178
	v_add_f32_e32 v179, 1.0, v179
	v_add_f32_e32 v180, 1.0, v180
	v_add_f32_e32 v181, 1.0, v181
	v_rcp_f32_e32 v178, v178
	v_rcp_f32_e32 v179, v179
	v_rcp_f32_e32 v180, v180
	v_rcp_f32_e32 v181, v181
	v_mul_f32_e32 v10, v10, v178
	v_mul_f32_e32 v11, v11, v179
	v_mul_f32_e32 v12, v12, v180
	v_mul_f32_e32 v13, v13, v181
	v_mul_f32_e32 v178, 0xbfb8aa3b, v6
	v_mul_f32_e32 v179, 0xbfb8aa3b, v7
	v_mul_f32_e32 v180, 0xbfb8aa3b, v8
	v_mul_f32_e32 v181, 0xbfb8aa3b, v9
	v_exp_f32_e32 v178, v178
	v_exp_f32_e32 v179, v179
	v_exp_f32_e32 v180, v180
	v_exp_f32_e32 v181, v181
	v_add_f32_e32 v178, 1.0, v178
	v_add_f32_e32 v179, 1.0, v179
	v_add_f32_e32 v180, 1.0, v180
	v_add_f32_e32 v181, 1.0, v181
	v_rcp_f32_e32 v178, v178
	v_rcp_f32_e32 v179, v179
	v_rcp_f32_e32 v180, v180
	v_rcp_f32_e32 v181, v181
	v_mul_f32_e32 v6, v6, v178
	v_mul_f32_e32 v7, v7, v179
	v_mul_f32_e32 v8, v8, v180
	v_mul_f32_e32 v9, v9, v181
	v_mul_f32_e32 v178, 0xbfb8aa3b, v2
	v_mul_f32_e32 v179, 0xbfb8aa3b, v3
	v_mul_f32_e32 v180, 0xbfb8aa3b, v4
	v_mul_f32_e32 v181, 0xbfb8aa3b, v5
	v_exp_f32_e32 v178, v178
	v_exp_f32_e32 v179, v179
	v_exp_f32_e32 v180, v180
	v_exp_f32_e32 v181, v181
	v_add_f32_e32 v178, 1.0, v178
	v_add_f32_e32 v179, 1.0, v179
	v_add_f32_e32 v180, 1.0, v180
	v_add_f32_e32 v181, 1.0, v181
	v_rcp_f32_e32 v178, v178
	v_rcp_f32_e32 v179, v179
	v_rcp_f32_e32 v180, v180
	v_rcp_f32_e32 v181, v181
	v_mul_f32_e32 v2, v2, v178
	v_mul_f32_e32 v3, v3, v179
	v_mul_f32_e32 v4, v4, v180
	v_mul_f32_e32 v5, v5, v181
	v_cvt_pk_bf16_f32 v164, v14, v15
	v_cvt_pk_bf16_f32 v165, v16, v17
	v_cvt_pk_bf16_f32 v166, v10, v11
	v_cvt_pk_bf16_f32 v167, v12, v13
	v_cvt_pk_bf16_f32 v168, v6, v7
	v_cvt_pk_bf16_f32 v169, v8, v9
	v_cvt_pk_bf16_f32 v170, v2, v3
	v_cvt_pk_bf16_f32 v171, v4, v5
	ds_write_b64 v136, v[164:165]
	v_xor_b32_e32 v173, 0x20, v136
	ds_write_b64 v173, v[166:167]
	v_xor_b32_e32 v174, 0x40, v136
	ds_write_b64 v174, v[168:169]
	v_xor_b32_e32 v175, 0x60, v136
	ds_write_b64 v175, v[170:171]
	ds_read_b128 v[156:159], v135
	ds_read_b128 v[160:163], v135 offset:1024
	s_waitcnt lgkmcnt(6)
	buffer_store_dwordx4 v[148:151], v139, s[44:47], s11 offen
	s_add_u32 s11, s11, 0x18000
	buffer_store_dwordx4 v[152:155], v139, s[44:47], s11 offen
	s_add_u32 s11, s11, 0x18000
	s_waitcnt lgkmcnt(0)
	buffer_store_dwordx4 v[156:159], v139, s[44:47], s11 offen
	s_add_u32 s11, s11, 0x18000
	buffer_store_dwordx4 v[160:163], v139, s[44:47], s11 offen
	s_branch .LBB0_141
